# swiglu: ssq panel staged into the LDS exchange area by LDS-DMA in the first K iteration; epilogue reads rstd inputs from LDS and drops the vmcnt(0) wait on the next unit's tile prefetch
# speedup vs baseline: 1.0173x; 1.0075x over previous
.Lswi_nobar:
.Lpeel_357:
	s_add_i32 s86, s42, 2
	s_add_u32 s29, s16, 0xfffc0080
	s_addc_u32 s37, s17, -1
	s_add_i32 s74, 0, 0x10000
	s_cmp_eq_u32 s20, s42
	s_cselect_b32 s73, s9, s37
	s_cselect_b32 s72, s13, s29
	v_add_u32_e32 v170, s74, v179
	s_cselect_b32 s43, s28, s57
	s_cselect_b32 s42, s39, s56
	s_add_i32 s29, 0, 0x14000
	ds_read_b128 v[130:133], v170
	ds_read_b128 v[180:183], v170 offset:1024
	ds_read_b128 v[184:187], v170 offset:2048
	ds_read_b128 v[188:191], v170 offset:3072
	v_add_u32_e32 v170, s29, v179
	ds_read_b128 v[192:195], v170
	ds_read_b128 v[196:199], v170 offset:1024
	ds_read_b128 v[204:207], v170 offset:2048
	ds_read_b128 v[208:211], v170 offset:3072
	s_add_i32 m0, s4, 0xc000
	ds_read_b128 v[212:215], v143
	ds_read_b128 v[216:219], v143 offset:1024
	ds_read_b128 v[220:223], v143 offset:2048
	ds_read_b128 v[224:227], v143 offset:3072
	ds_read_b128 v[228:231], v143 offset:4096
	ds_read_b128 v[232:235], v143 offset:5120
	ds_read_b128 v[236:239], v143 offset:6144
	ds_read_b128 v[240:243], v143 offset:7168
	global_load_lds_dwordx4 v174, s[16:17]
	s_add_i32 m0, s4, 0xe000
	s_nop 0
	global_load_lds_dwordx4 v176, s[16:17]
	s_waitcnt vmcnt(8)
	s_waitcnt lgkmcnt(0)
	s_setprio 1
	s_barrier
	v_mfma_f32_16x16x32_bf16 v[126:129], v[130:133], v[212:215], 0
	v_mfma_f32_16x16x32_bf16 v[118:121], v[184:187], v[212:215], 0
	v_mfma_f32_16x16x32_bf16 v[110:113], v[130:133], v[220:223], 0
	v_mfma_f32_16x16x32_bf16 v[102:105], v[184:187], v[220:223], 0
	v_mfma_f32_16x16x32_bf16 v[94:97], v[130:133], v[228:231], 0
	v_mfma_f32_16x16x32_bf16 v[86:89], v[184:187], v[228:231], 0
	v_mfma_f32_16x16x32_bf16 v[78:81], v[130:133], v[236:239], 0
	v_mfma_f32_16x16x32_bf16 v[70:73], v[184:187], v[236:239], 0
	v_mfma_f32_16x16x32_bf16 v[126:129], v[180:183], v[216:219], v[126:129]
	v_mfma_f32_16x16x32_bf16 v[118:121], v[188:191], v[216:219], v[118:121]
	v_mfma_f32_16x16x32_bf16 v[110:113], v[180:183], v[224:227], v[110:113]
	v_mfma_f32_16x16x32_bf16 v[102:105], v[188:191], v[224:227], v[102:105]
	v_mfma_f32_16x16x32_bf16 v[94:97], v[180:183], v[232:235], v[94:97]
	v_mfma_f32_16x16x32_bf16 v[86:89], v[188:191], v[232:235], v[86:89]
	v_mfma_f32_16x16x32_bf16 v[78:81], v[180:183], v[240:243], v[78:81]
	v_mfma_f32_16x16x32_bf16 v[70:73], v[188:191], v[240:243], v[70:73]
	v_mfma_f32_16x16x32_bf16 v[122:125], v[192:195], v[212:215], 0
	v_mfma_f32_16x16x32_bf16 v[114:117], v[204:207], v[212:215], 0
	v_mfma_f32_16x16x32_bf16 v[106:109], v[192:195], v[220:223], 0
	v_mfma_f32_16x16x32_bf16 v[98:101], v[204:207], v[220:223], 0
	v_mfma_f32_16x16x32_bf16 v[90:93], v[192:195], v[228:231], 0
	v_mfma_f32_16x16x32_bf16 v[82:85], v[204:207], v[228:231], 0
	v_mfma_f32_16x16x32_bf16 v[74:77], v[192:195], v[236:239], 0
	v_mfma_f32_16x16x32_bf16 v[66:69], v[204:207], v[236:239], 0
	v_mfma_f32_16x16x32_bf16 v[122:125], v[196:199], v[216:219], v[122:125]
	v_mfma_f32_16x16x32_bf16 v[114:117], v[208:211], v[216:219], v[114:117]
	v_mfma_f32_16x16x32_bf16 v[106:109], v[196:199], v[224:227], v[106:109]
	v_mfma_f32_16x16x32_bf16 v[98:101], v[208:211], v[224:227], v[98:101]
	v_mfma_f32_16x16x32_bf16 v[90:93], v[196:199], v[232:235], v[90:93]
	v_mfma_f32_16x16x32_bf16 v[82:85], v[208:211], v[232:235], v[82:85]
	v_mfma_f32_16x16x32_bf16 v[74:77], v[196:199], v[240:243], v[74:77]
	v_mfma_f32_16x16x32_bf16 v[66:69], v[208:211], v[240:243], v[66:69]
	s_barrier
	s_setprio 0
	s_add_i32 s37, s74, s84
	v_lshl_add_u64 v[244:245], s[42:43], 0, v[138:139]
	s_mov_b32 m0, s37
	ds_read_b128 v[212:215], v143 offset:16384
	ds_read_b128 v[216:219], v143 offset:17408
	ds_read_b128 v[220:223], v143 offset:18432
	ds_read_b128 v[224:227], v143 offset:19456
	ds_read_b128 v[228:231], v143 offset:20480
	ds_read_b128 v[232:235], v143 offset:21504
	ds_read_b128 v[236:239], v143 offset:22528
	ds_read_b128 v[240:243], v143 offset:23552
	global_load_lds_dwordx4 v[244:245], off
	s_add_i32 m0, s37, 0x2000
	s_add_u32 s74, s42, 0x40000
	v_lshl_add_u64 v[246:247], s[42:43], 0, v[134:135]
	s_addc_u32 s75, s43, 0
	s_add_i32 s29, s29, s84
	global_load_lds_dwordx4 v[246:247], off
	s_mov_b32 m0, s29
	v_lshl_add_u64 v[170:171], s[72:73], 0, v[136:137]
	global_load_lds_dwordx4 v138, s[74:75]
	s_add_i32 m0, s29, 0x2000
	s_nop 0
	global_load_lds_dwordx4 v134, s[74:75]
	v_lshl_add_u64 v[248:249], s[72:73], 0, v[140:141]
	s_mov_b32 m0, s4
	s_nop 0
	global_load_lds_dwordx4 v[248:249], off
	s_mov_b32 m0, s5
	s_nop 0
	global_load_lds_dwordx4 v[170:171], off
	s_lshl_b32 s101, s38, 14
	s_add_i32 s101, s101, s84
	s_add_u32 s100, s66, s101
	s_addc_u32 s101, s67, 0
	v_lshlrev_b32_e32 v172, 4, v163
	v_add_u32_e32 v173, 0x2000, v172
	s_add_i32 m0, s84, 0x20000
	s_nop 0
	global_load_lds_dwordx4 v172, s[100:101]
	s_add_i32 m0, s84, 0x22000
	s_nop 0
	global_load_lds_dwordx4 v173, s[100:101]
	s_waitcnt vmcnt(8)
	s_waitcnt lgkmcnt(0)
	s_setprio 1
	s_barrier
	v_mfma_f32_16x16x32_bf16 v[62:65], v[130:133], v[212:215], 0
	v_mfma_f32_16x16x32_bf16 v[54:57], v[184:187], v[212:215], 0
	v_mfma_f32_16x16x32_bf16 v[46:49], v[130:133], v[220:223], 0
	v_mfma_f32_16x16x32_bf16 v[38:41], v[184:187], v[220:223], 0
	v_mfma_f32_16x16x32_bf16 v[30:33], v[130:133], v[228:231], 0
	v_mfma_f32_16x16x32_bf16 v[22:25], v[184:187], v[228:231], 0
	v_mfma_f32_16x16x32_bf16 v[14:17], v[130:133], v[236:239], 0
	v_mfma_f32_16x16x32_bf16 v[6:9], v[184:187], v[236:239], 0
	v_mfma_f32_16x16x32_bf16 v[62:65], v[180:183], v[216:219], v[62:65]
	v_mfma_f32_16x16x32_bf16 v[54:57], v[188:191], v[216:219], v[54:57]
	v_mfma_f32_16x16x32_bf16 v[46:49], v[180:183], v[224:227], v[46:49]
	v_mfma_f32_16x16x32_bf16 v[38:41], v[188:191], v[224:227], v[38:41]
	v_mfma_f32_16x16x32_bf16 v[30:33], v[180:183], v[232:235], v[30:33]
	v_mfma_f32_16x16x32_bf16 v[22:25], v[188:191], v[232:235], v[22:25]
	v_mfma_f32_16x16x32_bf16 v[14:17], v[180:183], v[240:243], v[14:17]
	v_mfma_f32_16x16x32_bf16 v[6:9], v[188:191], v[240:243], v[6:9]
	v_mfma_f32_16x16x32_bf16 v[58:61], v[192:195], v[212:215], 0
	v_mfma_f32_16x16x32_bf16 v[50:53], v[204:207], v[212:215], 0
	v_mfma_f32_16x16x32_bf16 v[42:45], v[192:195], v[220:223], 0
	v_mfma_f32_16x16x32_bf16 v[34:37], v[204:207], v[220:223], 0
	v_mfma_f32_16x16x32_bf16 v[26:29], v[192:195], v[228:231], 0
	v_mfma_f32_16x16x32_bf16 v[18:21], v[204:207], v[228:231], 0
	v_mfma_f32_16x16x32_bf16 v[10:13], v[192:195], v[236:239], 0
	v_mfma_f32_16x16x32_bf16 v[2:5], v[204:207], v[236:239], 0
	v_mfma_f32_16x16x32_bf16 v[58:61], v[196:199], v[216:219], v[58:61]
	v_mfma_f32_16x16x32_bf16 v[50:53], v[208:211], v[216:219], v[50:53]
	v_mfma_f32_16x16x32_bf16 v[42:45], v[196:199], v[224:227], v[42:45]
	v_mfma_f32_16x16x32_bf16 v[34:37], v[208:211], v[224:227], v[34:37]
	v_mfma_f32_16x16x32_bf16 v[26:29], v[196:199], v[232:235], v[26:29]
	v_mfma_f32_16x16x32_bf16 v[18:21], v[208:211], v[232:235], v[18:21]
	v_mfma_f32_16x16x32_bf16 v[10:13], v[196:199], v[240:243], v[10:13]
	v_mfma_f32_16x16x32_bf16 v[2:5], v[208:211], v[240:243], v[2:5]
	s_barrier
	s_setprio 0
	s_add_i32 s29, 0, 0x18000
	v_add_u32_e32 v172, s29, v179
	s_add_i32 s37, 0, 0x1c000
	ds_read_b128 v[130:133], v172
	ds_read_b128 v[180:183], v172 offset:1024
	ds_read_b128 v[184:187], v172 offset:2048
	ds_read_b128 v[188:191], v172 offset:3072
	v_add_u32_e32 v172, s37, v179
	ds_read_b128 v[192:195], v172
	ds_read_b128 v[196:199], v172 offset:1024
	ds_read_b128 v[204:207], v172 offset:2048
	ds_read_b128 v[208:211], v172 offset:3072
	s_add_u32 s72, s72, 0x40000
	s_addc_u32 s73, s73, 0
	s_mov_b32 m0, s93
	ds_read_b128 v[212:215], v143 offset:32768
	ds_read_b128 v[216:219], v143 offset:33792
	ds_read_b128 v[220:223], v143 offset:34816
	ds_read_b128 v[224:227], v143 offset:35840
	ds_read_b128 v[228:231], v143 offset:36864
	ds_read_b128 v[232:235], v143 offset:37888
	ds_read_b128 v[236:239], v143 offset:38912
	ds_read_b128 v[240:243], v143 offset:39936
	global_load_lds_dwordx4 v140, s[72:73]
	s_mov_b32 m0, s33
	s_nop 0
	global_load_lds_dwordx4 v136, s[72:73]
	s_waitcnt vmcnt(8)
	s_waitcnt lgkmcnt(0)
	s_setprio 1
	s_barrier
	v_mfma_f32_16x16x32_bf16 v[126:129], v[130:133], v[212:215], v[126:129]
	v_mfma_f32_16x16x32_bf16 v[118:121], v[184:187], v[212:215], v[118:121]
	v_mfma_f32_16x16x32_bf16 v[110:113], v[130:133], v[220:223], v[110:113]
	v_mfma_f32_16x16x32_bf16 v[102:105], v[184:187], v[220:223], v[102:105]
	v_mfma_f32_16x16x32_bf16 v[94:97], v[130:133], v[228:231], v[94:97]
	v_mfma_f32_16x16x32_bf16 v[86:89], v[184:187], v[228:231], v[86:89]
	v_mfma_f32_16x16x32_bf16 v[78:81], v[130:133], v[236:239], v[78:81]
	v_mfma_f32_16x16x32_bf16 v[70:73], v[184:187], v[236:239], v[70:73]
	v_mfma_f32_16x16x32_bf16 v[126:129], v[180:183], v[216:219], v[126:129]
	v_mfma_f32_16x16x32_bf16 v[118:121], v[188:191], v[216:219], v[118:121]
	v_mfma_f32_16x16x32_bf16 v[110:113], v[180:183], v[224:227], v[110:113]
	v_mfma_f32_16x16x32_bf16 v[102:105], v[188:191], v[224:227], v[102:105]
	v_mfma_f32_16x16x32_bf16 v[94:97], v[180:183], v[232:235], v[94:97]
	v_mfma_f32_16x16x32_bf16 v[86:89], v[188:191], v[232:235], v[86:89]
	v_mfma_f32_16x16x32_bf16 v[78:81], v[180:183], v[240:243], v[78:81]
	v_mfma_f32_16x16x32_bf16 v[70:73], v[188:191], v[240:243], v[70:73]
	v_mfma_f32_16x16x32_bf16 v[122:125], v[192:195], v[212:215], v[122:125]
	v_mfma_f32_16x16x32_bf16 v[114:117], v[204:207], v[212:215], v[114:117]
	v_mfma_f32_16x16x32_bf16 v[106:109], v[192:195], v[220:223], v[106:109]
	v_mfma_f32_16x16x32_bf16 v[98:101], v[204:207], v[220:223], v[98:101]
	v_mfma_f32_16x16x32_bf16 v[90:93], v[192:195], v[228:231], v[90:93]
	v_mfma_f32_16x16x32_bf16 v[82:85], v[204:207], v[228:231], v[82:85]
	v_mfma_f32_16x16x32_bf16 v[74:77], v[192:195], v[236:239], v[74:77]
	v_mfma_f32_16x16x32_bf16 v[66:69], v[204:207], v[236:239], v[66:69]
	v_mfma_f32_16x16x32_bf16 v[122:125], v[196:199], v[216:219], v[122:125]
	v_mfma_f32_16x16x32_bf16 v[114:117], v[208:211], v[216:219], v[114:117]
	v_mfma_f32_16x16x32_bf16 v[106:109], v[196:199], v[224:227], v[106:109]
	v_mfma_f32_16x16x32_bf16 v[98:101], v[208:211], v[224:227], v[98:101]
	v_mfma_f32_16x16x32_bf16 v[90:93], v[196:199], v[232:235], v[90:93]
	v_mfma_f32_16x16x32_bf16 v[82:85], v[208:211], v[232:235], v[82:85]
	v_mfma_f32_16x16x32_bf16 v[74:77], v[196:199], v[240:243], v[74:77]
	v_mfma_f32_16x16x32_bf16 v[66:69], v[208:211], v[240:243], v[66:69]
	s_barrier
	s_setprio 0
	s_add_i32 s29, s29, s84
	v_lshl_add_u64 v[172:173], v[244:245], 0, s[24:25]
	s_mov_b32 m0, s29
	ds_read_b128 v[212:215], v143 offset:49152
	ds_read_b128 v[216:219], v143 offset:50176
	ds_read_b128 v[220:223], v143 offset:51200
	ds_read_b128 v[224:227], v143 offset:52224
	ds_read_b128 v[228:231], v143 offset:53248
	ds_read_b128 v[232:235], v143 offset:54272
	ds_read_b128 v[236:239], v143 offset:55296
	ds_read_b128 v[240:243], v143 offset:56320
	global_load_lds_dwordx4 v[172:173], off
	s_add_i32 m0, s29, 0x2000
	s_add_u32 s42, s42, 0x40080
	v_lshl_add_u64 v[172:173], v[246:247], 0, s[24:25]
	s_addc_u32 s43, s43, 0
	s_add_i32 s29, s37, s84
	global_load_lds_dwordx4 v[172:173], off
	s_mov_b32 m0, s29
	v_lshl_add_u64 v[170:171], v[170:171], 0, s[24:25]
	global_load_lds_dwordx4 v138, s[42:43]
	s_add_i32 m0, s29, 0x2000
	s_nop 0
	global_load_lds_dwordx4 v134, s[42:43]
	v_lshl_add_u64 v[172:173], v[248:249], 0, s[24:25]
	s_mov_b32 m0, s97
	s_nop 0
	global_load_lds_dwordx4 v[172:173], off
	s_mov_b32 m0, s3
	s_nop 0
	global_load_lds_dwordx4 v[170:171], off
	s_waitcnt vmcnt(8)
	s_waitcnt lgkmcnt(0)
	s_setprio 1
	s_barrier
	v_mfma_f32_16x16x32_bf16 v[62:65], v[130:133], v[212:215], v[62:65]
	v_mfma_f32_16x16x32_bf16 v[54:57], v[184:187], v[212:215], v[54:57]
	v_mfma_f32_16x16x32_bf16 v[46:49], v[130:133], v[220:223], v[46:49]
	v_mfma_f32_16x16x32_bf16 v[38:41], v[184:187], v[220:223], v[38:41]
	v_mfma_f32_16x16x32_bf16 v[30:33], v[130:133], v[228:231], v[30:33]
	v_mfma_f32_16x16x32_bf16 v[22:25], v[184:187], v[228:231], v[22:25]
	v_mfma_f32_16x16x32_bf16 v[14:17], v[130:133], v[236:239], v[14:17]
	v_mfma_f32_16x16x32_bf16 v[6:9], v[184:187], v[236:239], v[6:9]
	v_mfma_f32_16x16x32_bf16 v[62:65], v[180:183], v[216:219], v[62:65]
	v_mfma_f32_16x16x32_bf16 v[54:57], v[188:191], v[216:219], v[54:57]
	v_mfma_f32_16x16x32_bf16 v[46:49], v[180:183], v[224:227], v[46:49]
	v_mfma_f32_16x16x32_bf16 v[38:41], v[188:191], v[224:227], v[38:41]
	v_mfma_f32_16x16x32_bf16 v[30:33], v[180:183], v[232:235], v[30:33]
	v_mfma_f32_16x16x32_bf16 v[22:25], v[188:191], v[232:235], v[22:25]
	v_mfma_f32_16x16x32_bf16 v[14:17], v[180:183], v[240:243], v[14:17]
	v_mfma_f32_16x16x32_bf16 v[6:9], v[188:191], v[240:243], v[6:9]
	v_mfma_f32_16x16x32_bf16 v[58:61], v[192:195], v[212:215], v[58:61]
	v_mfma_f32_16x16x32_bf16 v[50:53], v[204:207], v[212:215], v[50:53]
	v_mfma_f32_16x16x32_bf16 v[42:45], v[192:195], v[220:223], v[42:45]
	v_mfma_f32_16x16x32_bf16 v[34:37], v[204:207], v[220:223], v[34:37]
	v_mfma_f32_16x16x32_bf16 v[26:29], v[192:195], v[228:231], v[26:29]
	v_mfma_f32_16x16x32_bf16 v[18:21], v[204:207], v[228:231], v[18:21]
	v_mfma_f32_16x16x32_bf16 v[10:13], v[192:195], v[236:239], v[10:13]
	v_mfma_f32_16x16x32_bf16 v[2:5], v[204:207], v[236:239], v[2:5]
	v_mfma_f32_16x16x32_bf16 v[58:61], v[196:199], v[216:219], v[58:61]
	v_mfma_f32_16x16x32_bf16 v[50:53], v[208:211], v[216:219], v[50:53]
	v_mfma_f32_16x16x32_bf16 v[42:45], v[196:199], v[224:227], v[42:45]
	v_mfma_f32_16x16x32_bf16 v[34:37], v[208:211], v[224:227], v[34:37]
	v_mfma_f32_16x16x32_bf16 v[26:29], v[196:199], v[232:235], v[26:29]
	v_mfma_f32_16x16x32_bf16 v[18:21], v[208:211], v[232:235], v[18:21]
	v_mfma_f32_16x16x32_bf16 v[10:13], v[196:199], v[240:243], v[10:13]
	v_mfma_f32_16x16x32_bf16 v[2:5], v[208:211], v[240:243], v[2:5]
	s_barrier
	s_setprio 0
	s_add_u32 s16, s16, 0x100
	s_addc_u32 s17, s17, 0
	s_add_u32 s56, s56, 0x100
	s_addc_u32 s57, s57, 0
	s_cmp_ge_i32 s86, s23
	s_mov_b32 s42, s86
	s_cbranch_scc0 .LBB7_357
	s_branch .Lpeelx_357

.Lswi_pref:
	v_and_b32_e32 v236, 0x30, v163
	v_lshl_add_u32 v236, v142, 6, v236
	v_add_u32_e32 v236, 0x20000, v236
	ds_read_b128 v[204:207], v236
	ds_read_b128 v[208:211], v236 offset:1024
	ds_read_b128 v[212:215], v236 offset:2048
	ds_read_b128 v[216:219], v236 offset:3072
	ds_read_b128 v[220:223], v236 offset:8192
	ds_read_b128 v[224:227], v236 offset:9216
	ds_read_b128 v[228:231], v236 offset:10240
	ds_read_b128 v[232:235], v236 offset:11264
	s_and_b64 vcc, exec, s[52:53]
	s_cbranch_vccz .LBB7_360

.LBB7_360:
	v_and_b32_e32 v131, 64, v163
	v_xor_b32_e32 v130, 16, v163
	v_add_u32_e32 v131, 64, v131
	v_cmp_lt_i32_e32 vcc, v130, v131
	v_lshl_add_u32 v132, s38, 8, v142
	v_ashrrev_i32_e32 v133, 31, v132
	v_cndmask_b32_e32 v130, v163, v130, vcc
	v_lshlrev_b32_e32 v183, 2, v130
	v_xor_b32_e32 v130, 32, v163
	v_cmp_lt_i32_e32 vcc, v130, v131
	v_or_b32_e32 v172, 16, v132
	v_ashrrev_i32_e32 v173, 31, v172
	v_cndmask_b32_e32 v130, v163, v130, vcc
	v_lshlrev_b32_e32 v181, 2, v130
	v_lshlrev_b64 v[130:131], 6, v[132:133]
	v_lshl_add_u64 v[130:131], v[144:145], 0, v[130:131]
	v_lshlrev_b64 v[172:173], 6, v[172:173]
	v_lshl_add_u64 v[172:173], v[144:145], 0, v[172:173]
	s_lshl_b32 s9, s10, 7
	s_mov_b32 s10, 0x358637bd
	v_mov_b64_e32 v[190:191], s[10:11]
	s_movk_i32 s10, 0x2000
	s_or_b32 s9, s9, s96
	s_ashr_i32 s16, s9, 6
	s_ashr_i32 s17, s16, 31
	s_mul_i32 s13, s38, 0x160000
	s_lshl_b64 s[16:17], s[16:17], 15
	s_add_u32 s9, s70, s13
	s_waitcnt lgkmcnt(0)
	v_mov_b64_e32 v[184:185], v[204:205]
	v_mov_b64_e32 v[186:187], v[206:207]
	v_mov_b32_e32 v170, v185
	v_mov_b32_e32 v171, v186
	v_mov_b32_e32 v185, v187
	v_pk_add_f32 v[170:171], v[170:171], v[184:185]
	v_mov_b64_e32 v[184:185], v[208:209]
	v_mov_b64_e32 v[186:187], v[210:211]
	v_mov_b32_e32 v172, v185
	v_mov_b32_e32 v173, v186
	v_mov_b32_e32 v185, v187
	v_pk_add_f32 v[172:173], v[172:173], v[184:185]
	v_mov_b32_e32 v185, v170
	v_mov_b32_e32 v184, v172
	v_mov_b32_e32 v170, v173
	v_pk_add_f32 v[170:171], v[184:185], v[170:171]
	v_mov_b32_e32 v173, v171
	s_nop 1
	v_permlane16_swap_b32_e32 v171, v173
	v_mov_b32_e32 v172, v170
	s_nop 1
	v_permlane16_swap_b32_e32 v170, v172
	s_waitcnt lgkmcnt(0)
	v_pk_add_f32 v[170:171], v[170:171], v[172:173]
	v_mov_b32_e32 v173, v171
	s_nop 1
	v_permlane32_swap_b32_e32 v171, v173
	v_mov_b32_e32 v172, v170
	s_nop 1
	v_permlane32_swap_b32_e32 v170, v172
	s_waitcnt lgkmcnt(0)
	v_pk_add_f32 v[170:171], v[170:171], v[172:173]
	s_nop 0
	v_pk_fma_f32 v[170:171], v[170:171], s[26:27], v[190:191] op_sel_hi:[1,0,0]
	v_mov_b64_e32 v[204:205], v[170:171]
	s_nop 0
	v_mul_f32_e32 v133, 0x4b800000, v171
	v_cmp_gt_f32_e64 s[42:43], s11, v171
	v_cmp_gt_f32_e32 vcc, s11, v170
	s_nop 0
	v_cndmask_b32_e64 v133, v171, v133, s[42:43]
	v_rsq_f32_e32 v133, v133
	s_nop 0
	v_mul_f32_e32 v171, 0x45800000, v133
	v_cndmask_b32_e64 v188, v133, v171, s[42:43]
	v_mul_f32_e32 v207, s30, v188
	v_mul_f32_e32 v133, 0x4b800000, v170
	v_cndmask_b32_e32 v133, v170, v133, vcc
	v_rsq_f32_e32 v133, v133
	s_nop 0
	v_mul_f32_e32 v170, 0x45800000, v133
	v_cndmask_b32_e32 v186, v133, v170, vcc
	v_mul_f32_e32 v206, s30, v186
	v_or_b32_e32 v170, 32, v132
	v_ashrrev_i32_e32 v171, 31, v170
	v_lshlrev_b64 v[170:171], 6, v[170:171]
	v_lshl_add_u64 v[170:171], v[144:145], 0, v[170:171]
	v_or_b32_e32 v132, 48, v132
	v_ashrrev_i32_e32 v133, 31, v132
	v_lshlrev_b64 v[132:133], 6, v[132:133]
	v_lshl_add_u64 v[132:133], v[144:145], 0, v[132:133]
	v_pk_mul_f32 v[122:123], v[126:127], v[122:123]
	v_pk_mul_f32 v[114:115], v[118:119], v[114:115]
	v_pk_mul_f32 v[106:107], v[110:111], v[106:107]
	v_pk_mul_f32 v[98:99], v[102:103], v[98:99]
	v_mov_b64_e32 v[192:193], v[212:213]
	v_mov_b64_e32 v[194:195], v[214:215]
	v_mov_b32_e32 v170, v193
	v_mov_b32_e32 v171, v194
	v_mov_b32_e32 v193, v195
	v_pk_add_f32 v[170:171], v[170:171], v[192:193]
	v_mov_b64_e32 v[192:193], v[216:217]
	v_mov_b64_e32 v[194:195], v[218:219]
	v_mov_b32_e32 v173, v170
	v_mov_b32_e32 v132, v193
	v_mov_b32_e32 v133, v194
	v_mov_b32_e32 v193, v195
	v_pk_add_f32 v[132:133], v[132:133], v[192:193]
	s_nop 0
	v_mov_b32_e32 v172, v132
	v_mov_b32_e32 v170, v133
	v_pk_add_f32 v[132:133], v[172:173], v[170:171]
	v_mov_b32_e32 v171, v133
	s_nop 1
	v_permlane16_swap_b32_e32 v133, v171
	v_mov_b32_e32 v170, v132
	s_nop 1
	v_permlane16_swap_b32_e32 v132, v170
	s_waitcnt lgkmcnt(0)
	v_pk_add_f32 v[132:133], v[132:133], v[170:171]
	v_mov_b32_e32 v171, v133
	s_nop 1
	v_permlane32_swap_b32_e32 v133, v171
	v_mov_b32_e32 v170, v132
	s_nop 1
	v_permlane32_swap_b32_e32 v132, v170
	s_waitcnt lgkmcnt(0)
	v_pk_add_f32 v[132:133], v[132:133], v[170:171]
	s_nop 0
	v_pk_fma_f32 v[132:133], v[132:133], s[26:27], v[190:191] op_sel_hi:[1,0,0]
	v_mov_b64_e32 v[212:213], v[132:133]
	s_nop 0
	v_mul_f32_e32 v170, 0x4b800000, v133
	v_cmp_gt_f32_e64 s[42:43], s11, v133
	v_cmp_gt_f32_e32 vcc, s11, v132
	s_nop 0
	v_cndmask_b32_e64 v133, v133, v170, s[42:43]
	v_rsq_f32_e32 v133, v133
	s_nop 0
	v_mul_f32_e32 v170, 0x45800000, v133
	v_cndmask_b32_e64 v184, v133, v170, s[42:43]
	v_mul_f32_e32 v215, s30, v184
	v_mul_f32_e32 v133, 0x4b800000, v132
	v_cndmask_b32_e32 v132, v132, v133, vcc
	v_rsq_f32_e32 v132, v132
	s_nop 0
	v_mul_f32_e32 v133, 0x45800000, v132
	v_cndmask_b32_e32 v182, v132, v133, vcc
	v_mul_f32_e32 v214, s30, v182
	v_add_co_u32_e32 v170, vcc, s10, v130
	s_mul_hi_i32 s10, s38, 0x160000
	s_nop 0
	v_addc_co_u32_e32 v171, vcc, 0, v131, vcc
	s_addc_u32 s10, s71, s10
	s_add_u32 s16, s9, s16
	s_addc_u32 s17, s10, s17
	v_pk_mul_f32 v[90:91], v[94:95], v[90:91]
	v_pk_mul_f32 v[82:83], v[86:87], v[82:83]
	v_pk_mul_f32 v[74:75], v[78:79], v[74:75]
	v_pk_mul_f32 v[66:67], v[70:71], v[66:67]
	v_mov_b64_e32 v[130:131], v[220:221]
	v_mov_b64_e32 v[132:133], v[222:223]
	v_mov_b32_e32 v172, v131
	v_mov_b32_e32 v173, v132
	v_mov_b32_e32 v131, v133
	v_pk_add_f32 v[172:173], v[172:173], v[130:131]
	v_mov_b64_e32 v[130:131], v[224:225]
	v_mov_b64_e32 v[132:133], v[226:227]
	v_mov_b32_e32 v192, v131
	v_mov_b32_e32 v193, v132
	v_mov_b32_e32 v131, v133
	v_pk_add_f32 v[130:131], v[192:193], v[130:131]
	v_mov_b32_e32 v133, v172
	v_mov_b32_e32 v132, v130
	v_mov_b32_e32 v172, v131
	v_pk_add_f32 v[130:131], v[132:133], v[172:173]
	v_mov_b32_e32 v133, v131
	s_nop 1
	v_permlane16_swap_b32_e32 v131, v133
	v_mov_b32_e32 v132, v130
	s_nop 1
	v_permlane16_swap_b32_e32 v130, v132
	s_waitcnt lgkmcnt(0)
	v_pk_add_f32 v[130:131], v[130:131], v[132:133]
	v_mov_b32_e32 v133, v131
	s_nop 1
	v_permlane32_swap_b32_e32 v131, v133
	v_mov_b32_e32 v132, v130
	s_nop 1
	v_permlane32_swap_b32_e32 v130, v132
	s_waitcnt lgkmcnt(0)
	v_pk_add_f32 v[130:131], v[130:131], v[132:133]
	s_nop 0
	v_pk_fma_f32 v[130:131], v[130:131], s[26:27], v[190:191] op_sel_hi:[1,0,0]
	v_mov_b64_e32 v[220:221], v[130:131]
	s_nop 0
	v_mul_f32_e32 v132, 0x4b800000, v131
	v_cmp_gt_f32_e64 s[42:43], s11, v131
	v_cmp_gt_f32_e32 vcc, s11, v130
	s_nop 0
	v_cndmask_b32_e64 v131, v131, v132, s[42:43]
	v_rsq_f32_e32 v131, v131
	s_nop 0
	v_mul_f32_e32 v132, 0x45800000, v131
	v_cndmask_b32_e64 v180, v131, v132, s[42:43]
	v_mul_f32_e32 v223, s30, v180
	v_mul_f32_e32 v131, 0x4b800000, v130
	v_cndmask_b32_e32 v130, v130, v131, vcc
	v_rsq_f32_e32 v130, v130
	s_nop 0
	v_mul_f32_e32 v131, 0x45800000, v130
	v_cndmask_b32_e32 v178, v130, v131, vcc
	v_mul_f32_e32 v222, s30, v178
	v_pk_mul_f32 v[58:59], v[62:63], v[58:59]
	v_pk_mul_f32 v[50:51], v[54:55], v[50:51]
	v_pk_mul_f32 v[42:43], v[46:47], v[42:43]
	v_pk_mul_f32 v[34:35], v[38:39], v[34:35]
	v_mov_b64_e32 v[130:131], v[228:229]
	v_mov_b64_e32 v[132:133], v[230:231]
	v_mov_b32_e32 v172, v131
	v_mov_b32_e32 v173, v132
	v_mov_b32_e32 v131, v133
	v_pk_add_f32 v[192:193], v[172:173], v[130:131]
	v_mov_b64_e32 v[130:131], v[232:233]
	v_mov_b64_e32 v[132:133], v[234:235]
	v_mov_b32_e32 v170, v131
	v_mov_b32_e32 v171, v132
	v_mov_b32_e32 v131, v133
	v_pk_add_f32 v[130:131], v[170:171], v[130:131]
	v_pk_mul_f32 v[170:171], v[126:127], v[206:207] op_sel:[0,1] op_sel_hi:[1,1]
	v_mov_b64_e32 v[126:127], v[128:129]
	v_exp_f32_e32 v170, v170
	v_pk_mul_f32 v[128:129], v[126:127], v[206:207] op_sel:[0,1] op_sel_hi:[1,1]
	v_exp_f32_e32 v171, v171
	v_exp_f32_e32 v128, v128
	v_exp_f32_e32 v129, v129
	v_pk_mul_f32 v[124:125], v[126:127], v[124:125]
	v_pk_fma_f32 v[170:171], v[170:171], v[204:205], v[204:205] op_sel:[0,1,1] op_sel_hi:[1,1,1]
	v_mov_b32_e32 v132, v130
	v_pk_fma_f32 v[128:129], v[128:129], v[204:205], v[204:205] op_sel:[0,1,1] op_sel_hi:[1,1,1]
	v_rcp_f32_e32 v170, v170
	v_rcp_f32_e32 v171, v171
	v_rcp_f32_e32 v128, v128
	v_rcp_f32_e32 v129, v129
	v_mov_b32_e32 v133, v192
	v_pk_mul_f32 v[122:123], v[122:123], v[170:171]
	v_mov_b32_e32 v192, v131
	v_pk_mul_f32 v[124:125], v[124:125], v[128:129]
	v_cvt_pk_bf16_f32 v122, v122, v123
	v_pk_add_f32 v[130:131], v[132:133], v[192:193]
	v_cvt_pk_bf16_f32 v123, v124, v125
	v_pk_mul_f32 v[124:125], v[118:119], v[206:207] op_sel:[0,1] op_sel_hi:[1,1]
	v_mov_b32_e32 v133, v131
	s_nop 1
	v_permlane16_swap_b32_e32 v131, v133
	v_exp_f32_e32 v124, v124
	v_exp_f32_e32 v125, v125
	v_mov_b32_e32 v132, v130
	s_nop 1
	v_permlane16_swap_b32_e32 v130, v132
	v_pk_fma_f32 v[124:125], v[124:125], v[204:205], v[204:205] op_sel:[0,1,1] op_sel_hi:[1,1,1]
	s_nop 0
	v_rcp_f32_e32 v124, v124
	v_rcp_f32_e32 v125, v125
	s_waitcnt lgkmcnt(0)
	v_pk_add_f32 v[130:131], v[130:131], v[132:133]
	v_mov_b32_e32 v133, v131
	s_nop 1
	v_permlane32_swap_b32_e32 v131, v133
	v_mov_b32_e32 v132, v130
	s_nop 1
	v_permlane32_swap_b32_e32 v130, v132
	v_pk_mul_f32 v[114:115], v[114:115], v[124:125]
	s_waitcnt lgkmcnt(0)
	v_pk_add_f32 v[130:131], v[130:131], v[132:133]
	v_cvt_pk_bf16_f32 v124, v114, v115
	v_mov_b64_e32 v[114:115], v[120:121]
	v_pk_fma_f32 v[130:131], v[130:131], s[26:27], v[190:191] op_sel_hi:[1,0,0]
	v_mov_b64_e32 v[228:229], v[130:131]
	v_pk_mul_f32 v[118:119], v[114:115], v[206:207] op_sel:[0,1] op_sel_hi:[1,1]
	v_pk_mul_f32 v[114:115], v[114:115], v[116:117]
	v_exp_f32_e32 v118, v118
	v_exp_f32_e32 v119, v119
	v_mul_f32_e32 v132, 0x4b800000, v131
	v_cmp_gt_f32_e64 s[42:43], s11, v131
	v_cmp_gt_f32_e32 vcc, s11, v130
	v_pk_fma_f32 v[118:119], v[118:119], v[204:205], v[204:205] op_sel:[0,1,1] op_sel_hi:[1,1,1]
	v_cndmask_b32_e64 v131, v131, v132, s[42:43]
	v_rcp_f32_e32 v118, v118
	v_rcp_f32_e32 v119, v119
	v_rsq_f32_e32 v131, v131
	v_pk_mul_f32 v[114:115], v[114:115], v[118:119]
	s_nop 0
	v_cvt_pk_bf16_f32 v125, v114, v115
	v_lshl_add_u64 v[114:115], s[16:17], 0, v[146:147]
	v_lshl_add_u64 v[114:115], v[114:115], 0, v[0:1]
	global_store_dwordx4 v[114:115], v[122:125], off nt
	v_pk_mul_f32 v[114:115], v[110:111], v[206:207] op_sel:[0,0] op_sel_hi:[1,0]
	v_mov_b64_e32 v[110:111], v[112:113]
	v_exp_f32_e32 v114, v114
	v_pk_mul_f32 v[112:113], v[110:111], v[206:207] op_sel:[0,0] op_sel_hi:[1,0]
	v_exp_f32_e32 v115, v115
	v_exp_f32_e32 v112, v112
	v_exp_f32_e32 v113, v113
	v_pk_mul_f32 v[108:109], v[110:111], v[108:109]
	v_pk_fma_f32 v[114:115], v[114:115], v[204:205], v[204:205] op_sel:[0,0,0] op_sel_hi:[1,0,0]
	v_pk_fma_f32 v[112:113], v[112:113], v[204:205], v[204:205] op_sel:[0,0,0] op_sel_hi:[1,0,0]
	v_rcp_f32_e32 v114, v114
	v_rcp_f32_e32 v115, v115
	v_rcp_f32_e32 v112, v112
	v_rcp_f32_e32 v113, v113
	v_mul_f32_e32 v132, 0x45800000, v131
	v_pk_mul_f32 v[106:107], v[106:107], v[114:115]
	v_cndmask_b32_e64 v132, v131, v132, s[42:43]
	v_mul_f32_e32 v231, s30, v132
	v_pk_mul_f32 v[108:109], v[108:109], v[112:113]
	v_cvt_pk_bf16_f32 v106, v106, v107
	v_cvt_pk_bf16_f32 v107, v108, v109
	v_pk_mul_f32 v[108:109], v[102:103], v[206:207] op_sel:[0,0] op_sel_hi:[1,0]
	v_exp_f32_e32 v108, v108
	v_exp_f32_e32 v109, v109
	v_pk_mul_f32 v[26:27], v[30:31], v[26:27]
	v_pk_fma_f32 v[108:109], v[108:109], v[204:205], v[204:205] op_sel:[0,0,0] op_sel_hi:[1,0,0]
	v_rcp_f32_e32 v108, v108
	v_rcp_f32_e32 v109, v109
	v_pk_mul_f32 v[18:19], v[22:23], v[18:19]
	v_mul_f32_e32 v131, 0x4b800000, v130
	v_cndmask_b32_e32 v130, v130, v131, vcc
	v_pk_mul_f32 v[98:99], v[98:99], v[108:109]
	v_rsq_f32_e32 v130, v130
	v_cvt_pk_bf16_f32 v108, v98, v99
	v_mov_b64_e32 v[98:99], v[104:105]
	v_pk_mul_f32 v[102:103], v[98:99], v[206:207] op_sel:[0,0] op_sel_hi:[1,0]
	v_pk_mul_f32 v[98:99], v[98:99], v[100:101]
	v_exp_f32_e32 v102, v102
	v_exp_f32_e32 v103, v103
	v_mul_f32_e32 v131, 0x45800000, v130
	v_cndmask_b32_e32 v130, v130, v131, vcc
	v_mul_f32_e32 v230, s30, v130
	v_pk_fma_f32 v[102:103], v[102:103], v[204:205], v[204:205] op_sel:[0,0,0] op_sel_hi:[1,0,0]
	v_rcp_f32_e32 v102, v102
	v_rcp_f32_e32 v103, v103
	v_pk_mul_f32 v[10:11], v[14:15], v[10:11]
	v_pk_mul_f32 v[98:99], v[98:99], v[102:103]
	v_cvt_pk_bf16_f32 v109, v98, v99
	v_lshl_add_u64 v[98:99], s[16:17], 0, v[148:149]
	v_lshl_add_u64 v[98:99], v[98:99], 0, v[0:1]
	global_store_dwordx4 v[98:99], v[106:109], off nt
	v_pk_mul_f32 v[98:99], v[94:95], v[214:215] op_sel:[0,1] op_sel_hi:[1,1]
	v_mov_b64_e32 v[94:95], v[96:97]
	v_exp_f32_e32 v98, v98
	v_pk_mul_f32 v[96:97], v[94:95], v[214:215] op_sel:[0,1] op_sel_hi:[1,1]
	v_exp_f32_e32 v99, v99
	v_exp_f32_e32 v96, v96
	v_exp_f32_e32 v97, v97
	v_pk_mul_f32 v[92:93], v[94:95], v[92:93]
	v_pk_fma_f32 v[98:99], v[98:99], v[212:213], v[212:213] op_sel:[0,1,1] op_sel_hi:[1,1,1]
	v_pk_fma_f32 v[96:97], v[96:97], v[212:213], v[212:213] op_sel:[0,1,1] op_sel_hi:[1,1,1]
	v_rcp_f32_e32 v98, v98
	v_rcp_f32_e32 v99, v99
	v_rcp_f32_e32 v96, v96
	v_rcp_f32_e32 v97, v97
	v_pk_mul_f32 v[2:3], v[6:7], v[2:3]
	v_pk_mul_f32 v[90:91], v[90:91], v[98:99]
	v_pk_mul_f32 v[92:93], v[92:93], v[96:97]
	v_cvt_pk_bf16_f32 v90, v90, v91
	s_andn2_b64 vcc, exec, s[40:41]
	v_cvt_pk_bf16_f32 v91, v92, v93
	v_pk_mul_f32 v[92:93], v[86:87], v[214:215] op_sel:[0,1] op_sel_hi:[1,1]
	s_nop 0
	v_exp_f32_e32 v92, v92
	v_exp_f32_e32 v93, v93
	s_nop 0
	v_pk_fma_f32 v[92:93], v[92:93], v[212:213], v[212:213] op_sel:[0,1,1] op_sel_hi:[1,1,1]
	s_nop 0
	v_rcp_f32_e32 v92, v92
	v_rcp_f32_e32 v93, v93
	s_nop 0
	v_pk_mul_f32 v[82:83], v[82:83], v[92:93]
	s_nop 0
	v_cvt_pk_bf16_f32 v92, v82, v83
	v_mov_b64_e32 v[82:83], v[88:89]
	s_nop 0
	v_pk_mul_f32 v[86:87], v[82:83], v[214:215] op_sel:[0,1] op_sel_hi:[1,1]
	v_pk_mul_f32 v[82:83], v[82:83], v[84:85]
	v_exp_f32_e32 v86, v86
	v_exp_f32_e32 v87, v87
	s_nop 0
	v_pk_fma_f32 v[86:87], v[86:87], v[212:213], v[212:213] op_sel:[0,1,1] op_sel_hi:[1,1,1]
	s_nop 0
	v_rcp_f32_e32 v86, v86
	v_rcp_f32_e32 v87, v87
	s_nop 0
	v_pk_mul_f32 v[82:83], v[82:83], v[86:87]
	s_nop 0
	v_cvt_pk_bf16_f32 v93, v82, v83
	v_lshl_add_u64 v[82:83], s[16:17], 0, v[150:151]
	v_lshl_add_u64 v[82:83], v[82:83], 0, v[0:1]
	global_store_dwordx4 v[82:83], v[90:93], off nt
	v_pk_mul_f32 v[82:83], v[78:79], v[214:215] op_sel:[0,0] op_sel_hi:[1,0]
	v_mov_b64_e32 v[78:79], v[80:81]
	v_exp_f32_e32 v82, v82
	v_pk_mul_f32 v[80:81], v[78:79], v[214:215] op_sel:[0,0] op_sel_hi:[1,0]
	v_exp_f32_e32 v83, v83
	v_exp_f32_e32 v80, v80
	v_exp_f32_e32 v81, v81
	v_pk_mul_f32 v[76:77], v[78:79], v[76:77]
	v_pk_fma_f32 v[82:83], v[82:83], v[212:213], v[212:213] op_sel:[0,0,0] op_sel_hi:[1,0,0]
	v_pk_fma_f32 v[80:81], v[80:81], v[212:213], v[212:213] op_sel:[0,0,0] op_sel_hi:[1,0,0]
	v_rcp_f32_e32 v82, v82
	v_rcp_f32_e32 v83, v83
	v_rcp_f32_e32 v80, v80
	v_rcp_f32_e32 v81, v81
	v_pk_mul_f32 v[74:75], v[74:75], v[82:83]
	s_nop 0
	v_cvt_pk_bf16_f32 v74, v74, v75
	v_pk_mul_f32 v[76:77], v[76:77], v[80:81]
	s_nop 0
	v_cvt_pk_bf16_f32 v75, v76, v77
	v_pk_mul_f32 v[76:77], v[70:71], v[214:215] op_sel:[0,0] op_sel_hi:[1,0]
	s_nop 0
	v_exp_f32_e32 v76, v76
	v_exp_f32_e32 v77, v77
	s_nop 0
	v_pk_fma_f32 v[76:77], v[76:77], v[212:213], v[212:213] op_sel:[0,0,0] op_sel_hi:[1,0,0]
	s_nop 0
	v_rcp_f32_e32 v76, v76
	v_rcp_f32_e32 v77, v77
	s_nop 0
	v_pk_mul_f32 v[66:67], v[66:67], v[76:77]
	s_nop 0
	v_cvt_pk_bf16_f32 v76, v66, v67
	v_mov_b64_e32 v[66:67], v[72:73]
	s_nop 0
	v_pk_mul_f32 v[70:71], v[66:67], v[214:215] op_sel:[0,0] op_sel_hi:[1,0]
	v_pk_mul_f32 v[66:67], v[66:67], v[68:69]
	v_exp_f32_e32 v70, v70
	v_exp_f32_e32 v71, v71
	s_nop 0
	v_pk_fma_f32 v[70:71], v[70:71], v[212:213], v[212:213] op_sel:[0,0,0] op_sel_hi:[1,0,0]
	s_nop 0
	v_rcp_f32_e32 v70, v70
	v_rcp_f32_e32 v71, v71
	s_nop 0
	v_pk_mul_f32 v[66:67], v[66:67], v[70:71]
	s_nop 0
	v_cvt_pk_bf16_f32 v77, v66, v67
	v_lshl_add_u64 v[66:67], s[16:17], 0, v[152:153]
	v_lshl_add_u64 v[66:67], v[66:67], 0, v[0:1]
	global_store_dwordx4 v[66:67], v[74:77], off nt
	v_pk_mul_f32 v[66:67], v[62:63], v[222:223] op_sel:[0,1] op_sel_hi:[1,1]
	v_mov_b64_e32 v[62:63], v[64:65]
	v_exp_f32_e32 v66, v66
	v_pk_mul_f32 v[64:65], v[62:63], v[222:223] op_sel:[0,1] op_sel_hi:[1,1]
	v_exp_f32_e32 v67, v67
	v_exp_f32_e32 v64, v64
	v_exp_f32_e32 v65, v65
	v_pk_mul_f32 v[60:61], v[62:63], v[60:61]
	v_pk_fma_f32 v[66:67], v[66:67], v[220:221], v[220:221] op_sel:[0,1,1] op_sel_hi:[1,1,1]
	v_pk_fma_f32 v[64:65], v[64:65], v[220:221], v[220:221] op_sel:[0,1,1] op_sel_hi:[1,1,1]
	v_rcp_f32_e32 v66, v66
	v_rcp_f32_e32 v67, v67
	v_rcp_f32_e32 v64, v64
	v_rcp_f32_e32 v65, v65
	v_pk_mul_f32 v[58:59], v[58:59], v[66:67]
	s_nop 0
	v_cvt_pk_bf16_f32 v58, v58, v59
	v_pk_mul_f32 v[60:61], v[60:61], v[64:65]
	s_nop 0
	v_cvt_pk_bf16_f32 v59, v60, v61
	v_pk_mul_f32 v[60:61], v[54:55], v[222:223] op_sel:[0,1] op_sel_hi:[1,1]
	s_nop 0
	v_exp_f32_e32 v60, v60
	v_exp_f32_e32 v61, v61
	s_nop 0
	v_pk_fma_f32 v[60:61], v[60:61], v[220:221], v[220:221] op_sel:[0,1,1] op_sel_hi:[1,1,1]
	s_nop 0
	v_rcp_f32_e32 v60, v60
	v_rcp_f32_e32 v61, v61
	s_nop 0
	v_pk_mul_f32 v[50:51], v[50:51], v[60:61]
	s_nop 0
	v_cvt_pk_bf16_f32 v60, v50, v51
	v_mov_b64_e32 v[50:51], v[56:57]
	s_nop 0
	v_pk_mul_f32 v[54:55], v[50:51], v[222:223] op_sel:[0,1] op_sel_hi:[1,1]
	v_pk_mul_f32 v[50:51], v[50:51], v[52:53]
	v_exp_f32_e32 v54, v54
	v_exp_f32_e32 v55, v55
	s_nop 0
	v_pk_fma_f32 v[54:55], v[54:55], v[220:221], v[220:221] op_sel:[0,1,1] op_sel_hi:[1,1,1]
	s_nop 0
	v_rcp_f32_e32 v54, v54
	v_rcp_f32_e32 v55, v55
	s_nop 0
	v_pk_mul_f32 v[50:51], v[50:51], v[54:55]
	s_nop 0
	v_cvt_pk_bf16_f32 v61, v50, v51
	v_lshl_add_u64 v[50:51], s[16:17], 0, v[154:155]
	v_lshl_add_u64 v[50:51], v[50:51], 0, v[0:1]
	global_store_dwordx4 v[50:51], v[58:61], off nt
	v_pk_mul_f32 v[50:51], v[46:47], v[222:223] op_sel:[0,0] op_sel_hi:[1,0]
	v_mov_b64_e32 v[46:47], v[48:49]
	v_exp_f32_e32 v50, v50
	v_pk_mul_f32 v[48:49], v[46:47], v[222:223] op_sel:[0,0] op_sel_hi:[1,0]
	v_exp_f32_e32 v51, v51
	v_exp_f32_e32 v48, v48
	v_exp_f32_e32 v49, v49
	v_pk_mul_f32 v[44:45], v[46:47], v[44:45]
	v_pk_fma_f32 v[50:51], v[50:51], v[220:221], v[220:221] op_sel:[0,0,0] op_sel_hi:[1,0,0]
	v_pk_fma_f32 v[48:49], v[48:49], v[220:221], v[220:221] op_sel:[0,0,0] op_sel_hi:[1,0,0]
	v_rcp_f32_e32 v50, v50
	v_rcp_f32_e32 v51, v51
	v_rcp_f32_e32 v48, v48
	v_rcp_f32_e32 v49, v49
	v_pk_mul_f32 v[42:43], v[42:43], v[50:51]
	s_nop 0
	v_cvt_pk_bf16_f32 v42, v42, v43
	v_pk_mul_f32 v[44:45], v[44:45], v[48:49]
	s_nop 0
	v_cvt_pk_bf16_f32 v43, v44, v45
	v_pk_mul_f32 v[44:45], v[38:39], v[222:223] op_sel:[0,0] op_sel_hi:[1,0]
	s_nop 0
	v_exp_f32_e32 v44, v44
	v_exp_f32_e32 v45, v45
	s_nop 0
	v_pk_fma_f32 v[44:45], v[44:45], v[220:221], v[220:221] op_sel:[0,0,0] op_sel_hi:[1,0,0]
	s_nop 0
	v_rcp_f32_e32 v44, v44
	v_rcp_f32_e32 v45, v45
	s_nop 0
	v_pk_mul_f32 v[34:35], v[34:35], v[44:45]
	s_nop 0
	v_cvt_pk_bf16_f32 v44, v34, v35
	v_mov_b64_e32 v[34:35], v[40:41]
	s_nop 0
	v_pk_mul_f32 v[38:39], v[34:35], v[222:223] op_sel:[0,0] op_sel_hi:[1,0]
	v_pk_mul_f32 v[34:35], v[34:35], v[36:37]
	v_exp_f32_e32 v38, v38
	v_exp_f32_e32 v39, v39
	s_nop 0
	v_pk_fma_f32 v[38:39], v[38:39], v[220:221], v[220:221] op_sel:[0,0,0] op_sel_hi:[1,0,0]
	s_nop 0
	v_rcp_f32_e32 v38, v38
	v_rcp_f32_e32 v39, v39
	s_nop 0
	v_pk_mul_f32 v[34:35], v[34:35], v[38:39]
	s_nop 0
	v_cvt_pk_bf16_f32 v45, v34, v35
	v_lshl_add_u64 v[34:35], s[16:17], 0, v[156:157]
	v_lshl_add_u64 v[34:35], v[34:35], 0, v[0:1]
	global_store_dwordx4 v[34:35], v[42:45], off nt
	v_pk_mul_f32 v[34:35], v[30:31], v[230:231] op_sel:[0,1] op_sel_hi:[1,1]
	v_mov_b64_e32 v[30:31], v[32:33]
	v_exp_f32_e32 v34, v34
	v_pk_mul_f32 v[32:33], v[30:31], v[230:231] op_sel:[0,1] op_sel_hi:[1,1]
	v_exp_f32_e32 v35, v35
	v_exp_f32_e32 v32, v32
	v_exp_f32_e32 v33, v33
	v_pk_mul_f32 v[28:29], v[30:31], v[28:29]
	v_pk_fma_f32 v[34:35], v[34:35], v[228:229], v[228:229] op_sel:[0,1,1] op_sel_hi:[1,1,1]
	v_pk_fma_f32 v[32:33], v[32:33], v[228:229], v[228:229] op_sel:[0,1,1] op_sel_hi:[1,1,1]
	v_rcp_f32_e32 v34, v34
	v_rcp_f32_e32 v35, v35
	v_rcp_f32_e32 v32, v32
	v_rcp_f32_e32 v33, v33
	v_pk_mul_f32 v[26:27], v[26:27], v[34:35]
	s_nop 0
	v_cvt_pk_bf16_f32 v26, v26, v27
	v_pk_mul_f32 v[28:29], v[28:29], v[32:33]
	s_nop 0
	v_cvt_pk_bf16_f32 v27, v28, v29
	v_pk_mul_f32 v[28:29], v[22:23], v[230:231] op_sel:[0,1] op_sel_hi:[1,1]
	s_nop 0
	v_exp_f32_e32 v28, v28
	v_exp_f32_e32 v29, v29
	s_nop 0
	v_pk_fma_f32 v[28:29], v[28:29], v[228:229], v[228:229] op_sel:[0,1,1] op_sel_hi:[1,1,1]
	s_nop 0
	v_rcp_f32_e32 v28, v28
	v_rcp_f32_e32 v29, v29
	s_nop 0
	v_pk_mul_f32 v[18:19], v[18:19], v[28:29]
	s_nop 0
	v_cvt_pk_bf16_f32 v28, v18, v19
	v_mov_b64_e32 v[18:19], v[24:25]
	s_nop 0
	v_pk_mul_f32 v[22:23], v[18:19], v[230:231] op_sel:[0,1] op_sel_hi:[1,1]
	v_pk_mul_f32 v[18:19], v[18:19], v[20:21]
	v_exp_f32_e32 v22, v22
	v_exp_f32_e32 v23, v23
	s_nop 0
	v_pk_fma_f32 v[22:23], v[22:23], v[228:229], v[228:229] op_sel:[0,1,1] op_sel_hi:[1,1,1]
	s_nop 0
	v_rcp_f32_e32 v22, v22
	v_rcp_f32_e32 v23, v23
	s_nop 0
	v_pk_mul_f32 v[18:19], v[18:19], v[22:23]
	s_nop 0
	v_cvt_pk_bf16_f32 v29, v18, v19
	v_lshl_add_u64 v[18:19], s[16:17], 0, v[158:159]
	v_lshl_add_u64 v[18:19], v[18:19], 0, v[0:1]
	global_store_dwordx4 v[18:19], v[26:29], off nt
	v_pk_mul_f32 v[18:19], v[14:15], v[230:231] op_sel:[0,0] op_sel_hi:[1,0]
	v_mov_b64_e32 v[14:15], v[16:17]
	v_exp_f32_e32 v18, v18
	v_pk_mul_f32 v[16:17], v[14:15], v[230:231] op_sel:[0,0] op_sel_hi:[1,0]
	v_exp_f32_e32 v19, v19
	v_exp_f32_e32 v16, v16
	v_exp_f32_e32 v17, v17
	v_pk_mul_f32 v[12:13], v[14:15], v[12:13]
	v_pk_fma_f32 v[18:19], v[18:19], v[228:229], v[228:229] op_sel:[0,0,0] op_sel_hi:[1,0,0]
	v_pk_fma_f32 v[16:17], v[16:17], v[228:229], v[228:229] op_sel:[0,0,0] op_sel_hi:[1,0,0]
	v_rcp_f32_e32 v18, v18
	v_rcp_f32_e32 v19, v19
	v_rcp_f32_e32 v16, v16
	v_rcp_f32_e32 v17, v17
	v_pk_mul_f32 v[10:11], v[10:11], v[18:19]
	s_nop 0
	v_cvt_pk_bf16_f32 v10, v10, v11
	v_pk_mul_f32 v[12:13], v[12:13], v[16:17]
	s_nop 0
	v_cvt_pk_bf16_f32 v11, v12, v13
	v_pk_mul_f32 v[12:13], v[6:7], v[230:231] op_sel:[0,0] op_sel_hi:[1,0]
	s_nop 0
	v_exp_f32_e32 v12, v12
	v_exp_f32_e32 v13, v13
	s_nop 0
	v_pk_fma_f32 v[12:13], v[12:13], v[228:229], v[228:229] op_sel:[0,0,0] op_sel_hi:[1,0,0]
	s_nop 0
	v_rcp_f32_e32 v12, v12
	v_rcp_f32_e32 v13, v13
	s_nop 0
	v_pk_mul_f32 v[2:3], v[2:3], v[12:13]
	s_nop 0
	v_cvt_pk_bf16_f32 v12, v2, v3
	v_mov_b64_e32 v[2:3], v[8:9]
	s_nop 0
	v_pk_mul_f32 v[6:7], v[2:3], v[230:231] op_sel:[0,0] op_sel_hi:[1,0]
	v_pk_mul_f32 v[2:3], v[2:3], v[4:5]
	v_exp_f32_e32 v6, v6
	v_exp_f32_e32 v7, v7
	s_nop 0
	v_pk_fma_f32 v[6:7], v[6:7], v[228:229], v[228:229] op_sel:[0,0,0] op_sel_hi:[1,0,0]
	s_nop 0
	v_rcp_f32_e32 v6, v6
	v_rcp_f32_e32 v7, v7
	s_nop 0
	v_pk_mul_f32 v[2:3], v[2:3], v[6:7]
	s_nop 0
	v_cvt_pk_bf16_f32 v13, v2, v3
	v_lshl_add_u64 v[2:3], s[16:17], 0, v[160:161]
	v_lshl_add_u64 v[2:3], v[2:3], 0, v[0:1]
	global_store_dwordx4 v[2:3], v[10:13], off nt
	s_mov_b64 s[16:17], -1
	s_cbranch_vccnz .LBB7_352
	s_andn2_b64 vcc, exec, s[50:51]
	s_cbranch_vccnz .LBB7_351
	s_branch .LBB7_351
